# g18 + P3 MLA items also distributed dynamically via zero-initialised atomic counter + LDS broadcast (reuses the item-end barrier)
# speedup vs baseline: 1.0141x; 1.0095x over previous
; DI float sigmoidf_(float x) { return 1.0f / (1.0f + __expf(-x)); }
; DI void store4(u16* dst, f32x4 v) { uint2 w; w.x = cvtpk(v[0], v[1]); w.y = cvtpk(v[2], v[3]); *(uint2*)dst = w; }
; DI f32x4 load4bf(const u16* src) { uint2 w = *(const uint2*)src; return (f32x4){bflo(w.x), bfhi(w.x), bflo(w.y), bfhi(w.y)}; }
; DI void mla_item(const Params& p, int it, unsigned char* smem, u16* mb_out) {
;     ...
;   const u16* mb = (const u16*)(p.ws + OFF_MB);
; #pragma unroll
;   for (int nt = 0; nt < 2; ++nt) {
;     float lt = l[nt]; lt += __shfl_xor(lt, 16); lt += __shfl_xor(lt, 32);
;     const float inv = 1.0f / lt;
;     const size_t t = tb0 + q0 + wave * 32 + nt * 16 + lr;
; #pragma unroll
;     for (int dt = 0; dt < 8; ++dt) {
;       const size_t oidx = t * 1024 + hp * 128 + dt * 16 + lq * 4;
;       const f32x4 gm = load4bf(mb + oidx);
;       const f32x4 ov = (dt < 4) ? Oa[dt & 3][nt] : Ob[dt & 3][nt];
;       f32x4 o;
; #pragma unroll
;       for (int j = 0; j < 4; ++j) o[j] = sigmoidf_(gm[j]) * ov[j] * inv;
;       store4(mb_out + oidx, o);
;     }
;   }
; DI void phase3(const Params& p, int bid, int nblk, unsigned char* smem, u16* mb_out) {
;     ...
;   for (int it = bid; it < 4096; it += nblk) { mla_item(p, it, smem, mb_out); __syncthreads(); }
.LBB0_418:
	v_readfirstlane_b32 s98, v218
	s_cmp_lg_u32 s98, 0
	s_cbranch_scc1 .Ldyn3_skip_a
	s_mov_b64 s[100:101], exec
	s_mov_b64 exec, 1
	v_mov_b32_e32 v137, 0x3fb04040
	v_mov_b32_e32 v138, 1
	global_atomic_add v136, v137, v138, s[42:43] sc0
	s_mov_b64 exec, s[100:101]
.Ldyn3_skip_a:
	v_lshl_add_u32 v0, s72, 7, v100
	s_waitcnt vmcnt(7)
	v_lshlrev_b64 v[68:69], 11, v[170:171]
	v_lshl_add_u64 v[2:3], s[2:3], 0, v[68:69]
	v_lshlrev_b64 v[70:71], 1, v[0:1]
	v_lshl_add_u64 v[2:3], v[2:3], 0, v[70:71]
	global_load_dwordx2 v[74:75], v[2:3], off
	s_waitcnt vmcnt(7)
	v_and_b32_e32 v72, 64, v220
	v_xor_b32_e32 v0, 16, v220
	v_add_u32_e32 v72, 64, v72
	v_cmp_lt_i32_e32 vcc, v0, v72
	v_xor_b32_e32 v73, 32, v220
	v_or_b32_e32 v68, 0x8000, v68
	v_cndmask_b32_e32 v0, v220, v0, vcc
	s_waitcnt vmcnt(6)
	v_lshlrev_b32_e32 v79, 2, v0
	ds_bpermute_b32 v0, v79, v169
	v_cmp_lt_i32_e32 vcc, v73, v72
	s_waitcnt lgkmcnt(0)
	v_add_f32_e32 v0, v169, v0
	v_cndmask_b32_e32 v72, v220, v73, vcc
	v_lshlrev_b32_e32 v78, 2, v72
	ds_bpermute_b32 v72, v78, v0
	s_waitcnt lgkmcnt(0)
	v_add_f32_e32 v0, v0, v72
	global_load_dwordx2 v[76:77], v[2:3], off offset:32
	global_load_dwordx2 v[80:81], v[2:3], off offset:64
	global_load_dwordx2 v[72:73], v[2:3], off offset:96
	s_waitcnt vmcnt(8)
	s_waitcnt vmcnt(7)
	v_rcp_f32_e32 v0, v0
	s_waitcnt vmcnt(3)
	v_lshlrev_b32_e32 v82, 16, v74
	v_and_b32_e32 v74, 0xffff0000, v74
	v_lshlrev_b32_e32 v83, 16, v75
	v_and_b32_e32 v75, 0xffff0000, v75
	v_mul_f32_e32 v82, 0xbfb8aa3b, v82
	v_mul_f32_e32 v87, 0xbfb8aa3b, v74
	v_mul_f32_e32 v88, 0xbfb8aa3b, v75
	v_exp_f32_e32 v74, v82
	v_exp_f32_e32 v75, v87
	v_mul_f32_e32 v83, 0xbfb8aa3b, v83
	v_exp_f32_e32 v82, v83
	v_exp_f32_e32 v83, v88
	v_pk_add_f32 v[74:75], v[74:75], 1.0 op_sel_hi:[1,0]
	v_pk_add_f32 v[82:83], v[82:83], 1.0 op_sel_hi:[1,0]
	s_mov_b64 vcc, s[0:1]
	v_rcp_f32_e32 v75, v75
	s_mov_b64 vcc, s[4:5]
	v_rcp_f32_e32 v74, v74
	s_mov_b64 vcc, s[6:7]
	v_pk_mul_f32 v[64:65], v[64:65], v[74:75]
	v_rcp_f32_e32 v75, v83
	v_rcp_f32_e32 v74, v82
	s_nop 0
	v_pk_mul_f32 v[66:67], v[66:67], v[74:75]
	s_waitcnt vmcnt(2)
	v_lshlrev_b32_e32 v74, 16, v76
	v_and_b32_e32 v75, 0xffff0000, v76
	v_mul_f32_e32 v74, 0xbfb8aa3b, v74
	v_mul_f32_e32 v75, 0xbfb8aa3b, v75
	v_exp_f32_e32 v74, v74
	v_exp_f32_e32 v75, v75
	v_pk_mul_f32 v[64:65], v[0:1], v[64:65] op_sel_hi:[0,1]
	v_pk_mul_f32 v[66:67], v[0:1], v[66:67] op_sel_hi:[0,1]
	v_cvt_pk_bf16_f32 v64, v64, v65
	v_cvt_pk_bf16_f32 v65, v66, v67
	v_pk_add_f32 v[66:67], v[74:75], 1.0 op_sel_hi:[1,0]
	global_store_dwordx2 v[2:3], v[64:65], off
	v_lshlrev_b32_e32 v64, 16, v77
	v_and_b32_e32 v76, 0xffff0000, v77
	v_mul_f32_e32 v64, 0xbfb8aa3b, v64
	v_rcp_f32_e32 v65, v67
	v_exp_f32_e32 v74, v64
	v_mul_f32_e32 v64, 0xbfb8aa3b, v76
	v_exp_f32_e32 v75, v64
	v_rcp_f32_e32 v64, v66
	v_pk_add_f32 v[74:75], v[74:75], 1.0 op_sel_hi:[1,0]
	v_pk_mul_f32 v[60:61], v[60:61], v[64:65]
	v_pk_mul_f32 v[60:61], v[0:1], v[60:61] op_sel_hi:[0,1]
	v_cvt_pk_bf16_f32 v60, v60, v61
	v_rcp_f32_e32 v65, v75
	v_rcp_f32_e32 v64, v74
	s_nop 0
	v_pk_mul_f32 v[62:63], v[62:63], v[64:65]
	s_waitcnt vmcnt(2)
	v_lshlrev_b32_e32 v64, 16, v80
	v_and_b32_e32 v65, 0xffff0000, v80
	v_mul_f32_e32 v64, 0xbfb8aa3b, v64
	v_mul_f32_e32 v65, 0xbfb8aa3b, v65
	v_exp_f32_e32 v64, v64
	v_exp_f32_e32 v65, v65
	v_pk_mul_f32 v[62:63], v[0:1], v[62:63] op_sel_hi:[0,1]
	v_cvt_pk_bf16_f32 v61, v62, v63
	global_store_dwordx2 v[2:3], v[60:61], off offset:32
	v_pk_add_f32 v[62:63], v[64:65], 1.0 op_sel_hi:[1,0]
	v_lshlrev_b32_e32 v60, 16, v81
	v_and_b32_e32 v66, 0xffff0000, v81
	v_mul_f32_e32 v60, 0xbfb8aa3b, v60
	v_rcp_f32_e32 v61, v63
	v_exp_f32_e32 v64, v60
	v_mul_f32_e32 v60, 0xbfb8aa3b, v66
	v_exp_f32_e32 v65, v60
	v_rcp_f32_e32 v60, v62
	v_pk_add_f32 v[64:65], v[64:65], 1.0 op_sel_hi:[1,0]
	v_pk_mul_f32 v[56:57], v[56:57], v[60:61]
	v_pk_mul_f32 v[60:61], v[0:1], v[56:57] op_sel_hi:[0,1]
	v_cvt_pk_bf16_f32 v60, v60, v61
	v_rcp_f32_e32 v57, v65
	v_rcp_f32_e32 v56, v64
	s_nop 0
	v_pk_mul_f32 v[58:59], v[58:59], v[56:57]
	global_load_dwordx2 v[56:57], v[2:3], off offset:128
	s_waitcnt vmcnt(3)
	v_lshlrev_b32_e32 v62, 16, v72
	v_and_b32_e32 v63, 0xffff0000, v72
	v_mul_f32_e32 v62, 0xbfb8aa3b, v62
	v_mul_f32_e32 v63, 0xbfb8aa3b, v63
	v_exp_f32_e32 v62, v62
	v_exp_f32_e32 v63, v63
	v_pk_mul_f32 v[58:59], v[0:1], v[58:59] op_sel_hi:[0,1]
	v_cvt_pk_bf16_f32 v61, v58, v59
	global_store_dwordx2 v[2:3], v[60:61], off offset:64
	v_pk_add_f32 v[58:59], v[62:63], 1.0 op_sel_hi:[1,0]
	v_lshlrev_b32_e32 v60, 16, v73
	v_and_b32_e32 v61, 0xffff0000, v73
	v_mul_f32_e32 v60, 0xbfb8aa3b, v60
	v_mul_f32_e32 v61, 0xbfb8aa3b, v61
	v_rcp_f32_e32 v59, v59
	v_exp_f32_e32 v60, v60
	v_exp_f32_e32 v61, v61
	s_nop 0
	v_pk_add_f32 v[60:61], v[60:61], 1.0 op_sel_hi:[1,0]
	v_rcp_f32_e32 v58, v58
	s_nop 0
	v_pk_mul_f32 v[52:53], v[52:53], v[58:59]
	v_rcp_f32_e32 v59, v61
	v_pk_mul_f32 v[52:53], v[0:1], v[52:53] op_sel_hi:[0,1]
	v_rcp_f32_e32 v58, v60
	s_nop 0
	v_pk_mul_f32 v[54:55], v[54:55], v[58:59]
	global_load_dwordx2 v[58:59], v[2:3], off offset:160
	global_load_dwordx2 v[60:61], v[2:3], off offset:192
	global_load_dwordx2 v[62:63], v[2:3], off offset:224
	v_pk_mul_f32 v[54:55], v[0:1], v[54:55] op_sel_hi:[0,1]
	v_cvt_pk_bf16_f32 v52, v52, v53
	v_cvt_pk_bf16_f32 v53, v54, v55
	global_store_dwordx2 v[2:3], v[52:53], off offset:96
	s_waitcnt vmcnt(5)
; DI float sigmoidf_(float x) { return 1.0f / (1.0f + __expf(-x)); }
; DI void store4(u16* dst, f32x4 v) { uint2 w; w.x = cvtpk(v[0], v[1]); w.y = cvtpk(v[2], v[3]); *(uint2*)dst = w; }
; DI f32x4 load4bf(const u16* src) { uint2 w = *(const uint2*)src; return (f32x4){bflo(w.x), bfhi(w.x), bflo(w.y), bfhi(w.y)}; }
; DI void mla_item(const Params& p, int it, unsigned char* smem, u16* mb_out) {
;     ...
;   for (int nt = 0; nt < 2; ++nt) {
;     float lt = l[nt]; lt += __shfl_xor(lt, 16); lt += __shfl_xor(lt, 32);
;     const float inv = 1.0f / lt;
;     const size_t t = tb0 + q0 + wave * 32 + nt * 16 + lr;
; #pragma unroll
;     for (int dt = 0; dt < 8; ++dt) {
;       const size_t oidx = t * 1024 + hp * 128 + dt * 16 + lq * 4;
;       const f32x4 gm = load4bf(mb + oidx);
;       const f32x4 ov = (dt < 4) ? Oa[dt & 3][nt] : Ob[dt & 3][nt];
;       f32x4 o;
; #pragma unroll
;       for (int j = 0; j < 4; ++j) o[j] = sigmoidf_(gm[j]) * ov[j] * inv;
;       store4(mb_out + oidx, o);
;     }
	v_lshlrev_b32_e32 v64, 16, v56
	v_and_b32_e32 v56, 0xffff0000, v56
	v_mul_f32_e32 v64, 0xbfb8aa3b, v64
	v_mul_f32_e32 v56, 0xbfb8aa3b, v56
	v_exp_f32_e32 v64, v64
	v_exp_f32_e32 v65, v56
	v_lshlrev_b32_e32 v52, 16, v57
	v_and_b32_e32 v57, 0xffff0000, v57
	v_mul_f32_e32 v52, 0xbfb8aa3b, v52
	v_pk_add_f32 v[54:55], v[64:65], 1.0 op_sel_hi:[1,0]
	s_nop 0
	s_nop 0
	v_rcp_f32_e32 v53, v55
	v_exp_f32_e32 v56, v52
	v_mul_f32_e32 v52, 0xbfb8aa3b, v57
	v_exp_f32_e32 v57, v52
	v_rcp_f32_e32 v52, v54
	v_pk_add_f32 v[56:57], v[56:57], 1.0 op_sel_hi:[1,0]
	v_pk_mul_f32 v[48:49], v[48:49], v[52:53]
	v_pk_mul_f32 v[48:49], v[0:1], v[48:49] op_sel_hi:[0,1]
	v_cvt_pk_bf16_f32 v48, v48, v49
	v_rcp_f32_e32 v53, v57
	v_rcp_f32_e32 v52, v56
	s_nop 0
	v_pk_mul_f32 v[50:51], v[50:51], v[52:53]
	s_waitcnt vmcnt(3)
	v_lshlrev_b32_e32 v52, 16, v58
	v_and_b32_e32 v53, 0xffff0000, v58
	v_mul_f32_e32 v52, 0xbfb8aa3b, v52
	v_mul_f32_e32 v53, 0xbfb8aa3b, v53
	v_exp_f32_e32 v52, v52
	v_exp_f32_e32 v53, v53
	v_pk_mul_f32 v[50:51], v[0:1], v[50:51] op_sel_hi:[0,1]
	v_cvt_pk_bf16_f32 v49, v50, v51
	global_store_dwordx2 v[2:3], v[48:49], off offset:128
	v_pk_add_f32 v[50:51], v[52:53], 1.0 op_sel_hi:[1,0]
	v_lshlrev_b32_e32 v48, 16, v59
	v_and_b32_e32 v54, 0xffff0000, v59
	v_mul_f32_e32 v48, 0xbfb8aa3b, v48
	v_rcp_f32_e32 v49, v51
	v_exp_f32_e32 v52, v48
	v_mul_f32_e32 v48, 0xbfb8aa3b, v54
	v_exp_f32_e32 v53, v48
	v_rcp_f32_e32 v48, v50
	v_pk_add_f32 v[52:53], v[52:53], 1.0 op_sel_hi:[1,0]
	v_pk_mul_f32 v[44:45], v[44:45], v[48:49]
	v_pk_mul_f32 v[44:45], v[0:1], v[44:45] op_sel_hi:[0,1]
	v_cvt_pk_bf16_f32 v44, v44, v45
	v_rcp_f32_e32 v49, v53
	v_rcp_f32_e32 v48, v52
	s_nop 0
	v_pk_mul_f32 v[46:47], v[46:47], v[48:49]
	s_waitcnt vmcnt(3)
	v_lshlrev_b32_e32 v48, 16, v60
	v_and_b32_e32 v49, 0xffff0000, v60
	v_mul_f32_e32 v48, 0xbfb8aa3b, v48
	v_mul_f32_e32 v49, 0xbfb8aa3b, v49
	v_exp_f32_e32 v48, v48
	v_exp_f32_e32 v49, v49
	v_pk_mul_f32 v[46:47], v[0:1], v[46:47] op_sel_hi:[0,1]
	v_cvt_pk_bf16_f32 v45, v46, v47
	global_store_dwordx2 v[2:3], v[44:45], off offset:160
	v_pk_add_f32 v[46:47], v[48:49], 1.0 op_sel_hi:[1,0]
	v_lshlrev_b32_e32 v44, 16, v61
	v_and_b32_e32 v50, 0xffff0000, v61
	v_mul_f32_e32 v44, 0xbfb8aa3b, v44
	v_rcp_f32_e32 v45, v47
	v_exp_f32_e32 v48, v44
	v_mul_f32_e32 v44, 0xbfb8aa3b, v50
	v_exp_f32_e32 v49, v44
	v_rcp_f32_e32 v44, v46
	v_pk_add_f32 v[48:49], v[48:49], 1.0 op_sel_hi:[1,0]
	v_pk_mul_f32 v[40:41], v[40:41], v[44:45]
	v_pk_mul_f32 v[40:41], v[0:1], v[40:41] op_sel_hi:[0,1]
	v_cvt_pk_bf16_f32 v40, v40, v41
	v_rcp_f32_e32 v45, v49
	v_rcp_f32_e32 v44, v48
	s_nop 0
	v_pk_mul_f32 v[42:43], v[42:43], v[44:45]
	s_waitcnt vmcnt(3)
	v_lshlrev_b32_e32 v44, 16, v62
	v_and_b32_e32 v45, 0xffff0000, v62
	v_mul_f32_e32 v44, 0xbfb8aa3b, v44
	v_mul_f32_e32 v45, 0xbfb8aa3b, v45
	v_exp_f32_e32 v44, v44
	v_exp_f32_e32 v45, v45
	v_pk_mul_f32 v[42:43], v[0:1], v[42:43] op_sel_hi:[0,1]
	v_cvt_pk_bf16_f32 v41, v42, v43
	global_store_dwordx2 v[2:3], v[40:41], off offset:192
	v_pk_add_f32 v[44:45], v[44:45], 1.0 op_sel_hi:[1,0]
	v_lshlrev_b32_e32 v48, 16, v63
	v_and_b32_e32 v49, 0xffff0000, v63
	v_lshl_add_u64 v[40:41], s[2:3], 0, v[68:69]
	v_lshl_add_u64 v[40:41], v[40:41], 0, v[70:71]
	global_load_dwordx2 v[42:43], v[40:41], off
	v_rcp_f32_e32 v45, v45
	v_mul_f32_e32 v46, 0xbfb8aa3b, v48
	v_mul_f32_e32 v47, 0xbfb8aa3b, v49
	v_exp_f32_e32 v46, v46
	v_exp_f32_e32 v47, v47
	v_rcp_f32_e32 v44, v44
	v_pk_add_f32 v[46:47], v[46:47], 1.0 op_sel_hi:[1,0]
	v_pk_mul_f32 v[36:37], v[36:37], v[44:45]
	v_pk_mul_f32 v[36:37], v[0:1], v[36:37] op_sel_hi:[0,1]
	v_cvt_pk_bf16_f32 v36, v36, v37
	v_rcp_f32_e32 v45, v47
	ds_bpermute_b32 v47, v79, v168
	s_waitcnt lgkmcnt(0)
	v_add_f32_e32 v47, v168, v47
	ds_bpermute_b32 v48, v78, v47
	v_rcp_f32_e32 v44, v46
	s_nop 0
	v_pk_mul_f32 v[38:39], v[38:39], v[44:45]
	s_waitcnt vmcnt(0)
	v_lshlrev_b32_e32 v44, 16, v42
	v_pk_mul_f32 v[38:39], v[0:1], v[38:39] op_sel_hi:[0,1]
	s_waitcnt lgkmcnt(0)
	v_add_f32_e32 v0, v47, v48
	v_cvt_pk_bf16_f32 v37, v38, v39
	global_store_dwordx2 v[2:3], v[36:37], off offset:224
	global_load_dwordx2 v[2:3], v[40:41], off offset:32
	global_load_dwordx2 v[38:39], v[40:41], off offset:64
	global_load_dwordx2 v[36:37], v[40:41], off offset:96
	v_and_b32_e32 v42, 0xffff0000, v42
	v_mul_f32_e32 v44, 0xbfb8aa3b, v44
	v_mul_f32_e32 v42, 0xbfb8aa3b, v42
	v_exp_f32_e32 v44, v44
	v_exp_f32_e32 v45, v42
	v_rcp_f32_e32 v0, v0
	v_pk_add_f32 v[44:45], v[44:45], 1.0 op_sel_hi:[1,0]
	v_lshlrev_b32_e32 v42, 16, v43
	v_and_b32_e32 v48, 0xffff0000, v43
	v_mul_f32_e32 v42, 0xbfb8aa3b, v42
	v_rcp_f32_e32 v43, v45
	v_exp_f32_e32 v46, v42
	v_mul_f32_e32 v42, 0xbfb8aa3b, v48
	v_exp_f32_e32 v47, v42
	v_rcp_f32_e32 v42, v44
	v_pk_add_f32 v[46:47], v[46:47], 1.0 op_sel_hi:[1,0]
	v_pk_mul_f32 v[32:33], v[32:33], v[42:43]
	v_pk_mul_f32 v[32:33], v[0:1], v[32:33] op_sel_hi:[0,1]
	v_cvt_pk_bf16_f32 v32, v32, v33
	v_rcp_f32_e32 v43, v47
	v_rcp_f32_e32 v42, v46
	s_nop 0
	v_pk_mul_f32 v[34:35], v[34:35], v[42:43]
	s_waitcnt vmcnt(2)
	v_lshlrev_b32_e32 v42, 16, v2
	v_and_b32_e32 v2, 0xffff0000, v2
	v_mul_f32_e32 v42, 0xbfb8aa3b, v42
	v_mul_f32_e32 v2, 0xbfb8aa3b, v2
	v_exp_f32_e32 v42, v42
	v_exp_f32_e32 v43, v2
	v_pk_mul_f32 v[34:35], v[0:1], v[34:35] op_sel_hi:[0,1]
	v_cvt_pk_bf16_f32 v33, v34, v35
	global_store_dwordx2 v[40:41], v[32:33], off
	v_pk_add_f32 v[34:35], v[42:43], 1.0 op_sel_hi:[1,0]
	v_lshlrev_b32_e32 v32, 16, v3
	v_and_b32_e32 v33, 0xffff0000, v3
	v_mul_f32_e32 v32, 0xbfb8aa3b, v32
	v_mul_f32_e32 v33, 0xbfb8aa3b, v33
	v_rcp_f32_e32 v3, v35
	v_exp_f32_e32 v32, v32
	v_exp_f32_e32 v33, v33
	s_nop 0
	v_pk_add_f32 v[32:33], v[32:33], 1.0 op_sel_hi:[1,0]
	v_rcp_f32_e32 v2, v34
	s_nop 0
	v_pk_mul_f32 v[2:3], v[28:29], v[2:3]
	v_rcp_f32_e32 v29, v33
	v_pk_mul_f32 v[2:3], v[0:1], v[2:3] op_sel_hi:[0,1]
	v_rcp_f32_e32 v28, v32
	s_nop 0
	v_pk_mul_f32 v[28:29], v[30:31], v[28:29]
	s_waitcnt vmcnt(2)
; DI float sigmoidf_(float x) { return 1.0f / (1.0f + __expf(-x)); }
; DI void store4(u16* dst, f32x4 v) { uint2 w; w.x = cvtpk(v[0], v[1]); w.y = cvtpk(v[2], v[3]); *(uint2*)dst = w; }
; DI f32x4 load4bf(const u16* src) { uint2 w = *(const uint2*)src; return (f32x4){bflo(w.x), bfhi(w.x), bflo(w.y), bfhi(w.y)}; }
; DI void mla_item(const Params& p, int it, unsigned char* smem, u16* mb_out) {
;     ...
; #pragma unroll
;     for (int dt = 0; dt < 8; ++dt) {
;       const size_t oidx = t * 1024 + hp * 128 + dt * 16 + lq * 4;
;       const f32x4 gm = load4bf(mb + oidx);
;       const f32x4 ov = (dt < 4) ? Oa[dt & 3][nt] : Ob[dt & 3][nt];
;       f32x4 o;
; #pragma unroll
;       for (int j = 0; j < 4; ++j) o[j] = sigmoidf_(gm[j]) * ov[j] * inv;
;       store4(mb_out + oidx, o);
;     }
;   }
; DI void phase3(const Params& p, int bid, int nblk, unsigned char* smem, u16* mb_out) {
;     ...
;   for (int it = bid; it < 4096; it += nblk) { mla_item(p, it, smem, mb_out); __syncthreads(); }
	v_lshlrev_b32_e32 v30, 16, v38
	v_and_b32_e32 v31, 0xffff0000, v38
	v_mul_f32_e32 v30, 0xbfb8aa3b, v30
	v_mul_f32_e32 v31, 0xbfb8aa3b, v31
	v_exp_f32_e32 v30, v30
	v_exp_f32_e32 v31, v31
	v_pk_mul_f32 v[28:29], v[0:1], v[28:29] op_sel_hi:[0,1]
	v_cvt_pk_bf16_f32 v2, v2, v3
	v_cvt_pk_bf16_f32 v3, v28, v29
	v_pk_add_f32 v[28:29], v[30:31], 1.0 op_sel_hi:[1,0]
	global_store_dwordx2 v[40:41], v[2:3], off offset:32
	v_lshlrev_b32_e32 v2, 16, v39
	v_and_b32_e32 v32, 0xffff0000, v39
	v_mul_f32_e32 v2, 0xbfb8aa3b, v2
	v_rcp_f32_e32 v3, v29
	v_exp_f32_e32 v30, v2
	v_mul_f32_e32 v2, 0xbfb8aa3b, v32
	v_exp_f32_e32 v31, v2
	v_rcp_f32_e32 v2, v28
	v_pk_add_f32 v[30:31], v[30:31], 1.0 op_sel_hi:[1,0]
	v_pk_mul_f32 v[2:3], v[24:25], v[2:3]
	v_pk_mul_f32 v[24:25], v[0:1], v[2:3] op_sel_hi:[0,1]
	v_cvt_pk_bf16_f32 v24, v24, v25
	v_rcp_f32_e32 v3, v31
	s_waitcnt vmcnt(2)
	v_lshlrev_b32_e32 v28, 16, v36
	v_and_b32_e32 v29, 0xffff0000, v36
	v_rcp_f32_e32 v2, v30
	v_mul_f32_e32 v28, 0xbfb8aa3b, v28
	v_mul_f32_e32 v29, 0xbfb8aa3b, v29
	v_pk_mul_f32 v[26:27], v[26:27], v[2:3]
	global_load_dwordx2 v[2:3], v[40:41], off offset:128
	v_exp_f32_e32 v28, v28
	v_exp_f32_e32 v29, v29
	v_pk_mul_f32 v[26:27], v[0:1], v[26:27] op_sel_hi:[0,1]
	v_cvt_pk_bf16_f32 v25, v26, v27
	global_store_dwordx2 v[40:41], v[24:25], off offset:64
	v_pk_add_f32 v[26:27], v[28:29], 1.0 op_sel_hi:[1,0]
	v_lshlrev_b32_e32 v24, 16, v37
	v_and_b32_e32 v30, 0xffff0000, v37
	v_mul_f32_e32 v24, 0xbfb8aa3b, v24
	v_rcp_f32_e32 v25, v27
	v_exp_f32_e32 v28, v24
	v_mul_f32_e32 v24, 0xbfb8aa3b, v30
	v_exp_f32_e32 v29, v24
	v_rcp_f32_e32 v24, v26
	v_pk_add_f32 v[28:29], v[28:29], 1.0 op_sel_hi:[1,0]
	v_pk_mul_f32 v[20:21], v[20:21], v[24:25]
	v_pk_mul_f32 v[20:21], v[0:1], v[20:21] op_sel_hi:[0,1]
	v_cvt_pk_bf16_f32 v20, v20, v21
	v_rcp_f32_e32 v25, v29
	v_rcp_f32_e32 v24, v28
	s_nop 0
	v_pk_mul_f32 v[22:23], v[22:23], v[24:25]
	global_load_dwordx2 v[24:25], v[40:41], off offset:160
	global_load_dwordx2 v[26:27], v[40:41], off offset:192
	global_load_dwordx2 v[28:29], v[40:41], off offset:224
	v_pk_mul_f32 v[22:23], v[0:1], v[22:23] op_sel_hi:[0,1]
	v_cvt_pk_bf16_f32 v21, v22, v23
	global_store_dwordx2 v[40:41], v[20:21], off offset:96
	s_waitcnt vmcnt(5)
	v_lshlrev_b32_e32 v30, 16, v2
	v_and_b32_e32 v2, 0xffff0000, v2
	v_mul_f32_e32 v30, 0xbfb8aa3b, v30
	v_mul_f32_e32 v2, 0xbfb8aa3b, v2
	v_exp_f32_e32 v30, v30
	v_exp_f32_e32 v31, v2
	v_lshlrev_b32_e32 v20, 16, v3
	v_and_b32_e32 v21, 0xffff0000, v3
	v_mul_f32_e32 v20, 0xbfb8aa3b, v20
	v_pk_add_f32 v[22:23], v[30:31], 1.0 op_sel_hi:[1,0]
	v_mul_f32_e32 v21, 0xbfb8aa3b, v21
	v_exp_f32_e32 v20, v20
	v_exp_f32_e32 v21, v21
	v_rcp_f32_e32 v3, v23
	v_pk_add_f32 v[20:21], v[20:21], 1.0 op_sel_hi:[1,0]
	v_rcp_f32_e32 v2, v22
	s_nop 0
	v_pk_mul_f32 v[2:3], v[16:17], v[2:3]
	v_rcp_f32_e32 v17, v21
	v_pk_mul_f32 v[2:3], v[0:1], v[2:3] op_sel_hi:[0,1]
	v_rcp_f32_e32 v16, v20
	s_nop 0
	v_pk_mul_f32 v[16:17], v[18:19], v[16:17]
	s_waitcnt vmcnt(3)
	v_lshlrev_b32_e32 v18, 16, v24
	v_and_b32_e32 v19, 0xffff0000, v24
	v_mul_f32_e32 v18, 0xbfb8aa3b, v18
	v_mul_f32_e32 v19, 0xbfb8aa3b, v19
	v_exp_f32_e32 v18, v18
	v_exp_f32_e32 v19, v19
	v_pk_mul_f32 v[16:17], v[0:1], v[16:17] op_sel_hi:[0,1]
	v_cvt_pk_bf16_f32 v2, v2, v3
	v_cvt_pk_bf16_f32 v3, v16, v17
	v_pk_add_f32 v[16:17], v[18:19], 1.0 op_sel_hi:[1,0]
	global_store_dwordx2 v[40:41], v[2:3], off offset:128
	v_lshlrev_b32_e32 v2, 16, v25
	v_and_b32_e32 v20, 0xffff0000, v25
	v_mul_f32_e32 v2, 0xbfb8aa3b, v2
	v_rcp_f32_e32 v3, v17
	v_exp_f32_e32 v18, v2
	v_mul_f32_e32 v2, 0xbfb8aa3b, v20
	v_exp_f32_e32 v19, v2
	v_rcp_f32_e32 v2, v16
	v_pk_add_f32 v[18:19], v[18:19], 1.0 op_sel_hi:[1,0]
	v_pk_mul_f32 v[2:3], v[12:13], v[2:3]
	v_pk_mul_f32 v[2:3], v[0:1], v[2:3] op_sel_hi:[0,1]
	v_cvt_pk_bf16_f32 v2, v2, v3
	v_rcp_f32_e32 v13, v19
	v_rcp_f32_e32 v12, v18
	s_nop 0
	v_pk_mul_f32 v[12:13], v[14:15], v[12:13]
	s_waitcnt vmcnt(3)
	v_lshlrev_b32_e32 v14, 16, v26
	v_and_b32_e32 v15, 0xffff0000, v26
	v_mul_f32_e32 v14, 0xbfb8aa3b, v14
	v_mul_f32_e32 v15, 0xbfb8aa3b, v15
	v_exp_f32_e32 v14, v14
	v_exp_f32_e32 v15, v15
	v_pk_mul_f32 v[12:13], v[0:1], v[12:13] op_sel_hi:[0,1]
	v_cvt_pk_bf16_f32 v3, v12, v13
	global_store_dwordx2 v[40:41], v[2:3], off offset:160
	v_pk_add_f32 v[12:13], v[14:15], 1.0 op_sel_hi:[1,0]
	v_lshlrev_b32_e32 v2, 16, v27
	v_and_b32_e32 v16, 0xffff0000, v27
	v_mul_f32_e32 v2, 0xbfb8aa3b, v2
	v_rcp_f32_e32 v3, v13
	v_exp_f32_e32 v14, v2
	v_mul_f32_e32 v2, 0xbfb8aa3b, v16
	v_exp_f32_e32 v15, v2
	v_rcp_f32_e32 v2, v12
	v_pk_add_f32 v[14:15], v[14:15], 1.0 op_sel_hi:[1,0]
	v_pk_mul_f32 v[2:3], v[8:9], v[2:3]
	v_pk_mul_f32 v[2:3], v[0:1], v[2:3] op_sel_hi:[0,1]
	v_cvt_pk_bf16_f32 v2, v2, v3
	v_rcp_f32_e32 v9, v15
	v_rcp_f32_e32 v8, v14
	s_nop 0
	v_pk_mul_f32 v[8:9], v[10:11], v[8:9]
	s_waitcnt vmcnt(3)
	v_lshlrev_b32_e32 v10, 16, v28
	v_and_b32_e32 v11, 0xffff0000, v28
	v_mul_f32_e32 v10, 0xbfb8aa3b, v10
	v_mul_f32_e32 v11, 0xbfb8aa3b, v11
	v_exp_f32_e32 v10, v10
	v_exp_f32_e32 v11, v11
	v_pk_mul_f32 v[8:9], v[0:1], v[8:9] op_sel_hi:[0,1]
	v_cvt_pk_bf16_f32 v3, v8, v9
	global_store_dwordx2 v[40:41], v[2:3], off offset:192
	v_pk_add_f32 v[8:9], v[10:11], 1.0 op_sel_hi:[1,0]
	v_lshlrev_b32_e32 v2, 16, v29
	v_and_b32_e32 v12, 0xffff0000, v29
	v_mul_f32_e32 v2, 0xbfb8aa3b, v2
	v_rcp_f32_e32 v3, v9
	v_exp_f32_e32 v10, v2
	v_mul_f32_e32 v2, 0xbfb8aa3b, v12
	v_exp_f32_e32 v11, v2
	v_rcp_f32_e32 v2, v8
	v_pk_add_f32 v[10:11], v[10:11], 1.0 op_sel_hi:[1,0]
	v_pk_mul_f32 v[2:3], v[4:5], v[2:3]
	v_pk_mul_f32 v[2:3], v[0:1], v[2:3] op_sel_hi:[0,1]
	v_cvt_pk_bf16_f32 v2, v2, v3
	v_rcp_f32_e32 v5, v11
	v_readlane_b32 s0, v245, 23
	v_rcp_f32_e32 v4, v10
	s_nop 0
	v_pk_mul_f32 v[4:5], v[6:7], v[4:5]
	v_pk_mul_f32 v[4:5], v[0:1], v[4:5] op_sel_hi:[0,1]
	v_cvt_pk_bf16_f32 v3, v4, v5
	global_store_dwordx2 v[40:41], v[2:3], off offset:224
	v_mov_b32_e32 v139, 0x8100
	v_readfirstlane_b32 s98, v218
	s_cmp_lg_u32 s98, 0
	s_cbranch_scc1 .Ldyn3_skip_b
	s_waitcnt vmcnt(5)
	s_mov_b64 s[100:101], exec
	s_mov_b64 exec, 1
	ds_write_b32 v139, v136
	s_waitcnt lgkmcnt(0)
	s_mov_b64 exec, s[100:101]
.Ldyn3_skip_b:
	s_barrier
	ds_read_b32 v136, v139
	s_waitcnt lgkmcnt(0)
	v_readfirstlane_b32 s71, v136
	s_add_i32 s71, s71, s92
	s_lshl_b32 s70, s71, 8
	s_cmpk_lt_i32 s71, 0x1000
	v_readlane_b32 s1, v245, 24
	s_cbranch_scc0 .LBB0_463
